# adds: EpiResNorm (P10) pass 1 with 8-12 residual loads in flight leaving v in the accumulators, pass 2 without residual re-read; EpiRes (P7) prompt epilogue loads pipelined
# speedup vs baseline: 1.0565x; 1.0228x over previous
;     __device__ __forceinline__ void operator()(const f32x4 (&acc)[2][2][4][2], const Unit& u, int wr, int wc, int fr, int fq) const {
;         const int row0 = u.pm * BM + wr * 64 + fr, col0 = u.pn * BM + wc * 32 + 4 * fq;
;         if (u.pm >= 32) { store_partials(acc, u, row0, col0, gate, part); return; }
;         f32x4 gv[2][2];
; #pragma unroll
;         for (int bj = 0; bj < 2; ++bj)
; #pragma unroll
;             for (int n = 0; n < 2; ++n) gv[bj][n] = *(const f32x4*)(gate + (size_t)128 * NMOD + col0 + bj * HALF + n * 16);
;         int roff = row0 * D + col0; asm volatile("" : "+v"(roff));
; #pragma unroll
;         for (int am = 0; am < 4; ++am) { f32x4 rv[2][2][2];
; #pragma unroll
;             for (int m2 = 0; m2 < 2; ++m2)
; #pragma unroll
;                 for (int bj = 0; bj < 2; ++bj)
; #pragma unroll
;                     for (int n = 0; n < 2; ++n) rv[m2][bj][n] = *(const f32x4*)(res0 + (roff + ((am >> 1) * HALF + ((am & 1) * 2 + m2) * 16) * D + bj * HALF + n * 16));
; #pragma unroll
;             for (int m2 = 0; m2 < 2; ++m2)
; #pragma unroll
;                 for (int bj = 0; bj < 2; ++bj)
; #pragma unroll
;                     for (int n = 0; n < 2; ++n) *(f32x4*)(out + (roff + ((am >> 1) * HALF + ((am & 1) * 2 + m2) * 16) * D + bj * HALF + n * 16)) = rv[m2][bj][n] + gv[bj][n] * acc[am >> 1][bj][(am & 1) * 2 + m2][n]; }
.LBB0_886:
	v_ashrrev_i32_e32 v163, 31, v162
	v_lshl_add_u64 v[128:129], v[162:163], 2, s[12:13]
	v_lshl_add_u32 v164, v168, 11, v162
	global_load_dwordx4 v[140:143], v[128:129], off
	global_load_dwordx4 v[136:139], v[128:129], off offset:64
	global_load_dwordx4 v[132:135], v[128:129], off offset:512
	s_nop 0
	global_load_dwordx4 v[128:131], v[128:129], off offset:576
	v_readlane_b32 s64, v245, 37
	v_readlane_b32 s65, v245, 38
	v_readlane_b32 s66, v245, 39
	v_readlane_b32 s67, v245, 40
	v_readlane_b32 s68, v245, 41
	v_readlane_b32 s69, v245, 42
	v_readlane_b32 s70, v245, 43
	v_readlane_b32 s71, v245, 44
	v_readlane_b32 s72, v245, 45
	v_readlane_b32 s73, v245, 46
	v_readlane_b32 s74, v245, 47
	v_readlane_b32 s75, v245, 48
	v_readlane_b32 s76, v245, 49
	v_readlane_b32 s77, v245, 50
	v_readlane_b32 s78, v245, 51
	v_readlane_b32 s79, v245, 52
	v_ashrrev_i32_e32 v165, 31, v164
	v_lshlrev_b64 v[222:223], 2, v[164:165]
	s_nop 1
	v_lshl_add_u64 v[220:221], s[64:65], 0, v[222:223]
	v_lshl_add_u64 v[222:223], s[6:7], 0, v[222:223]
	global_load_dwordx4 v[172:175], v[220:221], off
	global_load_dwordx4 v[176:179], v[220:221], off offset:64
	global_load_dwordx4 v[180:183], v[220:221], off offset:512
	global_load_dwordx4 v[184:187], v[220:221], off offset:576
	v_add_co_u32_e32 v224, vcc, 0x20000, v220
	s_nop 1
	v_addc_co_u32_e32 v225, vcc, 0, v221, vcc
	global_load_dwordx4 v[188:191], v[224:225], off
	global_load_dwordx4 v[192:195], v[224:225], off offset:64
	global_load_dwordx4 v[196:199], v[224:225], off offset:512
	global_load_dwordx4 v[200:203], v[224:225], off offset:576
	v_add_co_u32_e32 v224, vcc, 0x40000, v220
	s_nop 1
	v_addc_co_u32_e32 v225, vcc, 0, v221, vcc
	global_load_dwordx4 v[204:207], v[224:225], off
	global_load_dwordx4 v[208:211], v[224:225], off offset:64
	global_load_dwordx4 v[212:215], v[224:225], off offset:512
	global_load_dwordx4 v[216:219], v[224:225], off offset:576
	s_waitcnt vmcnt(8)
	v_pk_fma_f32 v[174:175], v[126:127], v[142:143], v[174:175]
	v_pk_fma_f32 v[172:173], v[124:125], v[140:141], v[172:173]
	global_store_dwordx4 v[222:223], v[172:175], off
	v_pk_fma_f32 v[178:179], v[122:123], v[138:139], v[178:179]
	v_pk_fma_f32 v[176:177], v[120:121], v[136:137], v[176:177]
	global_store_dwordx4 v[222:223], v[176:179], off offset:64
	v_pk_fma_f32 v[182:183], v[110:111], v[134:135], v[182:183]
	v_pk_fma_f32 v[180:181], v[108:109], v[132:133], v[180:181]
	global_store_dwordx4 v[222:223], v[180:183], off offset:512
	v_pk_fma_f32 v[186:187], v[106:107], v[130:131], v[186:187]
	v_pk_fma_f32 v[184:185], v[104:105], v[128:129], v[184:185]
	global_store_dwordx4 v[222:223], v[184:187], off offset:576
	v_add_co_u32_e32 v224, vcc, 0x60000, v220
	s_nop 1
	v_addc_co_u32_e32 v225, vcc, 0, v221, vcc
	global_load_dwordx4 v[172:175], v[224:225], off
	global_load_dwordx4 v[176:179], v[224:225], off offset:64
	global_load_dwordx4 v[180:183], v[224:225], off offset:512
	global_load_dwordx4 v[184:187], v[224:225], off offset:576
	s_waitcnt vmcnt(12)
	v_add_co_u32_e32 v226, vcc, 0x20000, v222
	s_nop 1
	v_addc_co_u32_e32 v227, vcc, 0, v223, vcc
	v_pk_fma_f32 v[190:191], v[118:119], v[142:143], v[190:191]
	v_pk_fma_f32 v[188:189], v[116:117], v[140:141], v[188:189]
	global_store_dwordx4 v[226:227], v[188:191], off
	v_pk_fma_f32 v[194:195], v[114:115], v[138:139], v[194:195]
	v_pk_fma_f32 v[192:193], v[112:113], v[136:137], v[192:193]
	global_store_dwordx4 v[226:227], v[192:195], off offset:64
	v_pk_fma_f32 v[198:199], v[102:103], v[134:135], v[198:199]
	v_pk_fma_f32 v[196:197], v[100:101], v[132:133], v[196:197]
	global_store_dwordx4 v[226:227], v[196:199], off offset:512
	v_pk_fma_f32 v[202:203], v[98:99], v[130:131], v[202:203]
	v_pk_fma_f32 v[200:201], v[96:97], v[128:129], v[200:201]
	global_store_dwordx4 v[226:227], v[200:203], off offset:576
	v_add_co_u32_e32 v224, vcc, 0x100000, v220
	s_nop 1
	v_addc_co_u32_e32 v225, vcc, 0, v221, vcc
	global_load_dwordx4 v[188:191], v[224:225], off
	global_load_dwordx4 v[192:195], v[224:225], off offset:64
	global_load_dwordx4 v[196:199], v[224:225], off offset:512
	global_load_dwordx4 v[200:203], v[224:225], off offset:576
	s_waitcnt vmcnt(16)
	v_add_co_u32_e32 v226, vcc, 0x40000, v222
	s_nop 1
	v_addc_co_u32_e32 v227, vcc, 0, v223, vcc
	v_pk_fma_f32 v[206:207], v[94:95], v[142:143], v[206:207]
	v_pk_fma_f32 v[204:205], v[92:93], v[140:141], v[204:205]
	global_store_dwordx4 v[226:227], v[204:207], off
	v_pk_fma_f32 v[210:211], v[90:91], v[138:139], v[210:211]
	v_pk_fma_f32 v[208:209], v[88:89], v[136:137], v[208:209]
	global_store_dwordx4 v[226:227], v[208:211], off offset:64
	v_pk_fma_f32 v[214:215], v[78:79], v[134:135], v[214:215]
	v_pk_fma_f32 v[212:213], v[76:77], v[132:133], v[212:213]
	global_store_dwordx4 v[226:227], v[212:215], off offset:512
	v_pk_fma_f32 v[218:219], v[74:75], v[130:131], v[218:219]
	v_pk_fma_f32 v[216:217], v[72:73], v[128:129], v[216:217]
	global_store_dwordx4 v[226:227], v[216:219], off offset:576
	v_add_co_u32_e32 v224, vcc, 0x120000, v220
	s_nop 1
	v_addc_co_u32_e32 v225, vcc, 0, v221, vcc
	global_load_dwordx4 v[204:207], v[224:225], off
	global_load_dwordx4 v[208:211], v[224:225], off offset:64
	global_load_dwordx4 v[212:215], v[224:225], off offset:512
	global_load_dwordx4 v[216:219], v[224:225], off offset:576
	s_waitcnt vmcnt(16)
;     __device__ __forceinline__ void operator()(const f32x4 (&acc)[2][2][4][2], const Unit& u, int wr, int wc, int fr, int fq) const {
;     ...
;         for (int am = 0; am < 4; ++am) { f32x4 rv[2][2][2];
; #pragma unroll
;             for (int m2 = 0; m2 < 2; ++m2)
; #pragma unroll
;                 for (int bj = 0; bj < 2; ++bj)
; #pragma unroll
;                     for (int n = 0; n < 2; ++n) rv[m2][bj][n] = *(const f32x4*)(res0 + (roff + ((am >> 1) * HALF + ((am & 1) * 2 + m2) * 16) * D + bj * HALF + n * 16));
; #pragma unroll
;             for (int m2 = 0; m2 < 2; ++m2)
; #pragma unroll
;                 for (int bj = 0; bj < 2; ++bj)
; #pragma unroll
;                     for (int n = 0; n < 2; ++n) *(f32x4*)(out + (roff + ((am >> 1) * HALF + ((am & 1) * 2 + m2) * 16) * D + bj * HALF + n * 16)) = rv[m2][bj][n] + gv[bj][n] * acc[am >> 1][bj][(am & 1) * 2 + m2][n]; }
	v_add_co_u32_e32 v226, vcc, 0x60000, v222
	s_nop 1
	v_addc_co_u32_e32 v227, vcc, 0, v223, vcc
	v_pk_fma_f32 v[174:175], v[86:87], v[142:143], v[174:175]
	v_pk_fma_f32 v[172:173], v[84:85], v[140:141], v[172:173]
	global_store_dwordx4 v[226:227], v[172:175], off
	v_pk_fma_f32 v[178:179], v[82:83], v[138:139], v[178:179]
	v_pk_fma_f32 v[176:177], v[80:81], v[136:137], v[176:177]
	global_store_dwordx4 v[226:227], v[176:179], off offset:64
	v_pk_fma_f32 v[182:183], v[70:71], v[134:135], v[182:183]
	v_pk_fma_f32 v[180:181], v[68:69], v[132:133], v[180:181]
	global_store_dwordx4 v[226:227], v[180:183], off offset:512
	v_pk_fma_f32 v[186:187], v[66:67], v[130:131], v[186:187]
	v_pk_fma_f32 v[184:185], v[64:65], v[128:129], v[184:185]
	global_store_dwordx4 v[226:227], v[184:187], off offset:576
	v_add_co_u32_e32 v224, vcc, 0x140000, v220
	s_nop 1
	v_addc_co_u32_e32 v225, vcc, 0, v221, vcc
	global_load_dwordx4 v[172:175], v[224:225], off
	global_load_dwordx4 v[176:179], v[224:225], off offset:64
	global_load_dwordx4 v[180:183], v[224:225], off offset:512
	global_load_dwordx4 v[184:187], v[224:225], off offset:576
	s_waitcnt vmcnt(16)
	v_add_co_u32_e32 v226, vcc, 0x100000, v222
	s_nop 1
	v_addc_co_u32_e32 v227, vcc, 0, v223, vcc
	v_pk_fma_f32 v[190:191], v[62:63], v[142:143], v[190:191]
	v_pk_fma_f32 v[188:189], v[60:61], v[140:141], v[188:189]
	global_store_dwordx4 v[226:227], v[188:191], off
	v_pk_fma_f32 v[194:195], v[58:59], v[138:139], v[194:195]
	v_pk_fma_f32 v[192:193], v[56:57], v[136:137], v[192:193]
	global_store_dwordx4 v[226:227], v[192:195], off offset:64
	v_pk_fma_f32 v[198:199], v[46:47], v[134:135], v[198:199]
	v_pk_fma_f32 v[196:197], v[44:45], v[132:133], v[196:197]
	global_store_dwordx4 v[226:227], v[196:199], off offset:512
	v_pk_fma_f32 v[202:203], v[42:43], v[130:131], v[202:203]
	v_pk_fma_f32 v[200:201], v[40:41], v[128:129], v[200:201]
	global_store_dwordx4 v[226:227], v[200:203], off offset:576
	v_add_co_u32_e32 v224, vcc, 0x160000, v220
	s_nop 1
	v_addc_co_u32_e32 v225, vcc, 0, v221, vcc
	global_load_dwordx4 v[188:191], v[224:225], off
	global_load_dwordx4 v[192:195], v[224:225], off offset:64
	global_load_dwordx4 v[196:199], v[224:225], off offset:512
	global_load_dwordx4 v[200:203], v[224:225], off offset:576
	s_waitcnt vmcnt(16)
	v_add_co_u32_e32 v226, vcc, 0x120000, v222
	s_nop 1
	v_addc_co_u32_e32 v227, vcc, 0, v223, vcc
	v_pk_fma_f32 v[206:207], v[54:55], v[142:143], v[206:207]
	v_pk_fma_f32 v[204:205], v[52:53], v[140:141], v[204:205]
	global_store_dwordx4 v[226:227], v[204:207], off
	v_pk_fma_f32 v[210:211], v[50:51], v[138:139], v[210:211]
	v_pk_fma_f32 v[208:209], v[48:49], v[136:137], v[208:209]
	global_store_dwordx4 v[226:227], v[208:211], off offset:64
	v_pk_fma_f32 v[214:215], v[38:39], v[134:135], v[214:215]
	v_pk_fma_f32 v[212:213], v[36:37], v[132:133], v[212:213]
	global_store_dwordx4 v[226:227], v[212:215], off offset:512
	v_pk_fma_f32 v[218:219], v[34:35], v[130:131], v[218:219]
	v_pk_fma_f32 v[216:217], v[32:33], v[128:129], v[216:217]
	global_store_dwordx4 v[226:227], v[216:219], off offset:576
	s_waitcnt vmcnt(12)
	v_add_co_u32_e32 v226, vcc, 0x140000, v222
	s_nop 1
	v_addc_co_u32_e32 v227, vcc, 0, v223, vcc
	v_pk_fma_f32 v[174:175], v[30:31], v[142:143], v[174:175]
	v_pk_fma_f32 v[172:173], v[28:29], v[140:141], v[172:173]
	global_store_dwordx4 v[226:227], v[172:175], off
	v_pk_fma_f32 v[178:179], v[26:27], v[138:139], v[178:179]
	v_pk_fma_f32 v[176:177], v[24:25], v[136:137], v[176:177]
	global_store_dwordx4 v[226:227], v[176:179], off offset:64
	v_pk_fma_f32 v[182:183], v[14:15], v[134:135], v[182:183]
	v_pk_fma_f32 v[180:181], v[12:13], v[132:133], v[180:181]
	global_store_dwordx4 v[226:227], v[180:183], off offset:512
	v_pk_fma_f32 v[186:187], v[10:11], v[130:131], v[186:187]
	v_pk_fma_f32 v[184:185], v[8:9], v[128:129], v[184:185]
	global_store_dwordx4 v[226:227], v[184:187], off offset:576
	s_waitcnt vmcnt(8)
	v_add_co_u32_e32 v226, vcc, 0x160000, v222
	s_nop 1
	v_addc_co_u32_e32 v227, vcc, 0, v223, vcc
	v_pk_fma_f32 v[190:191], v[22:23], v[142:143], v[190:191]
	v_pk_fma_f32 v[188:189], v[20:21], v[140:141], v[188:189]
	global_store_dwordx4 v[226:227], v[188:191], off
	v_pk_fma_f32 v[194:195], v[18:19], v[138:139], v[194:195]
	v_pk_fma_f32 v[192:193], v[16:17], v[136:137], v[192:193]
	global_store_dwordx4 v[226:227], v[192:195], off offset:64
	v_pk_fma_f32 v[198:199], v[6:7], v[134:135], v[198:199]
	v_pk_fma_f32 v[196:197], v[4:5], v[132:133], v[196:197]
	global_store_dwordx4 v[226:227], v[196:199], off offset:512
	v_pk_fma_f32 v[202:203], v[2:3], v[130:131], v[202:203]
	v_pk_fma_f32 v[200:201], v[0:1], v[128:129], v[200:201]
	global_store_dwordx4 v[226:227], v[200:203], off offset:576
	s_cbranch_execnz .LBB0_885

;     __device__ __forceinline__ void operator()(const f32x4 (&acc)[2][2][4][2], const Unit& u, int wr, int wc, int fr, int fq) const {
;     ...
;         const float* gp = gate + (size_t)128 * NMOD;
;         int roff = row0 * D + col0; asm volatile("" : "+v"(roff));
; #pragma unroll
;         for (int ai = 0; ai < 2; ++ai)
; #pragma unroll
;             for (int m = 0; m < 4; ++m) { const int ro = roff + (ai * HALF + m * 16) * D; float ps = 0.f;
; #pragma unroll
;                 for (int bj = 0; bj < 2; ++bj)
; #pragma unroll
;                     for (int n = 0; n < 2; ++n) { const int o = bj * HALF + n * 16; const f32x4 rv = *(const f32x4*)(res0 + (ro + o)), gv = *(const f32x4*)(gp + (col0 + o));
;                         const f32x4 v = rv + gv * acc[ai][bj][m][n]; ps += v[0] * v[0] + v[1] * v[1] + v[2] * v[2] + v[3] * v[3]; }
;                 ps += __shfl_xor(ps, 16); ps += __shfl_xor(ps, 32);
;                 if (fq == 0) red[(ai * HALF + wr * 64 + m * 16 + fr) * 4 + wc] = ps; }
.LBB0_1144:
	v_lshl_add_u32 v190, s26, 8, v161
	v_lshl_or_b32 v174, s27, 8, v182
	s_cmp_lt_i32 s26, 32
	s_mov_b64 s[34:35], -1
	s_cbranch_scc0 .LBB0_1182
	v_lshl_add_u32 v172, v190, 11, v174
	v_mov_b32_e32 v128, v172
	v_ashrrev_i32_e32 v175, 31, v174
	v_lshl_add_u64 v[144:145], v[174:175], 2, s[14:15]
	v_ashrrev_i32_e32 v129, 31, v128
	v_lshl_add_u64 v[146:147], v[128:129], 2, s[8:9]
	global_load_dwordx4 v[128:131], v[144:145], off
	global_load_dwordx4 v[132:135], v[144:145], off offset:64
	global_load_dwordx4 v[136:139], v[144:145], off offset:512
	global_load_dwordx4 v[140:143], v[144:145], off offset:576
	global_load_dwordx4 v[192:195], v[146:147], off
	global_load_dwordx4 v[196:199], v[146:147], off offset:64
	global_load_dwordx4 v[200:203], v[146:147], off offset:512
	global_load_dwordx4 v[204:207], v[146:147], off offset:576
	v_add_co_u32_e32 v176, vcc, 0x20000, v146
	s_nop 1
	v_addc_co_u32_e32 v177, vcc, 0, v147, vcc
	global_load_dwordx4 v[208:211], v[176:177], off
	global_load_dwordx4 v[212:215], v[176:177], off offset:64
	global_load_dwordx4 v[216:219], v[176:177], off offset:512
	global_load_dwordx4 v[220:223], v[176:177], off offset:576
	v_add_co_u32_e32 v176, vcc, 0x40000, v146
	s_nop 1
	v_addc_co_u32_e32 v177, vcc, 0, v147, vcc
	global_load_dwordx4 v[224:227], v[176:177], off
	global_load_dwordx4 v[228:231], v[176:177], off offset:64
	global_load_dwordx4 v[232:235], v[176:177], off offset:512
	global_load_dwordx4 v[152:155], v[176:177], off offset:576
	v_xor_b32_e32 v148, 16, v188
	v_xor_b32_e32 v149, 32, v188
	v_lshlrev_b32_e32 v148, 2, v148
	v_lshlrev_b32_e32 v149, 2, v149
	s_waitcnt vmcnt(8)
	v_pk_fma_f32 v[124:125], v[124:125], v[128:129], v[192:193]
	v_pk_fma_f32 v[126:127], v[126:127], v[130:131], v[194:195]
	v_pk_fma_f32 v[120:121], v[120:121], v[132:133], v[196:197]
	v_pk_fma_f32 v[122:123], v[122:123], v[134:135], v[198:199]
	v_pk_fma_f32 v[108:109], v[108:109], v[136:137], v[200:201]
	v_pk_fma_f32 v[110:111], v[110:111], v[138:139], v[202:203]
	v_pk_fma_f32 v[104:105], v[104:105], v[140:141], v[204:205]
	v_pk_fma_f32 v[106:107], v[106:107], v[142:143], v[206:207]
	v_mul_f32_e32 v150, v125, v125
	v_mul_f32_e32 v151, v121, v121
	v_mul_f32_e32 v173, v109, v109
	v_fmac_f32_e32 v150, v124, v124
	v_fmac_f32_e32 v151, v120, v120
	v_mul_f32_e32 v236, v105, v105
	v_fmac_f32_e32 v173, v108, v108
	v_fmac_f32_e32 v150, v126, v126
	v_fmac_f32_e32 v151, v122, v122
	v_fmac_f32_e32 v236, v104, v104
	v_fmac_f32_e32 v173, v110, v110
	v_fmac_f32_e32 v150, v127, v127
	v_fmac_f32_e32 v151, v123, v123
	v_fmac_f32_e32 v236, v106, v106
	v_fmac_f32_e32 v173, v111, v111
	v_add_f32_e32 v150, v150, v151
	v_add_f32_e32 v150, v150, v173
	v_fmac_f32_e32 v236, v107, v107
	v_add_f32_e32 v150, v150, v236
	ds_bpermute_b32 v151, v148, v150
	s_waitcnt lgkmcnt(0)
	v_add_f32_e32 v150, v150, v151
	ds_bpermute_b32 v151, v149, v150
	s_waitcnt lgkmcnt(0)
	v_add_f32_e32 v150, v150, v151
	s_and_saveexec_b64 s[30:31], s[0:1]
	ds_write_b32 v189, v150
	s_or_b64 exec, exec, s[30:31]
	v_add_co_u32_e32 v176, vcc, 0x60000, v146
	s_nop 1
	v_addc_co_u32_e32 v177, vcc, 0, v147, vcc
	global_load_dwordx4 v[192:195], v[176:177], off
	global_load_dwordx4 v[196:199], v[176:177], off offset:64
	global_load_dwordx4 v[200:203], v[176:177], off offset:512
	global_load_dwordx4 v[204:207], v[176:177], off offset:576
	s_waitcnt vmcnt(8)
	v_pk_fma_f32 v[116:117], v[116:117], v[128:129], v[208:209]
	v_pk_fma_f32 v[118:119], v[118:119], v[130:131], v[210:211]
	v_pk_fma_f32 v[112:113], v[112:113], v[132:133], v[212:213]
	v_pk_fma_f32 v[114:115], v[114:115], v[134:135], v[214:215]
	v_pk_fma_f32 v[100:101], v[100:101], v[136:137], v[216:217]
	v_pk_fma_f32 v[102:103], v[102:103], v[138:139], v[218:219]
	v_pk_fma_f32 v[96:97], v[96:97], v[140:141], v[220:221]
	v_pk_fma_f32 v[98:99], v[98:99], v[142:143], v[222:223]
	v_mul_f32_e32 v150, v117, v117
	v_mul_f32_e32 v151, v113, v113
	v_mul_f32_e32 v173, v101, v101
	v_fmac_f32_e32 v150, v116, v116
	v_fmac_f32_e32 v151, v112, v112
	v_mul_f32_e32 v236, v97, v97
	v_fmac_f32_e32 v173, v100, v100
	v_fmac_f32_e32 v150, v118, v118
	v_fmac_f32_e32 v151, v114, v114
	v_fmac_f32_e32 v236, v96, v96
	v_fmac_f32_e32 v173, v102, v102
	v_fmac_f32_e32 v150, v119, v119
	v_fmac_f32_e32 v151, v115, v115
	v_fmac_f32_e32 v236, v98, v98
	v_fmac_f32_e32 v173, v103, v103
	v_add_f32_e32 v150, v150, v151
	v_add_f32_e32 v150, v150, v173
	v_fmac_f32_e32 v236, v99, v99
	v_add_f32_e32 v150, v150, v236
	ds_bpermute_b32 v151, v148, v150
	s_waitcnt lgkmcnt(0)
	v_add_f32_e32 v150, v150, v151
	ds_bpermute_b32 v151, v149, v150
	s_waitcnt lgkmcnt(0)
	v_add_f32_e32 v150, v150, v151
	s_and_saveexec_b64 s[30:31], s[0:1]
	ds_write_b32 v189, v150 offset:256
	s_or_b64 exec, exec, s[30:31]
	v_add_co_u32_e32 v176, vcc, 0x100000, v146
	s_nop 1
	v_addc_co_u32_e32 v177, vcc, 0, v147, vcc
	global_load_dwordx4 v[208:211], v[176:177], off
	global_load_dwordx4 v[212:215], v[176:177], off offset:64
	global_load_dwordx4 v[216:219], v[176:177], off offset:512
	global_load_dwordx4 v[220:223], v[176:177], off offset:576
	s_waitcnt vmcnt(8)
	v_pk_fma_f32 v[92:93], v[92:93], v[128:129], v[224:225]
	v_pk_fma_f32 v[94:95], v[94:95], v[130:131], v[226:227]
	v_pk_fma_f32 v[88:89], v[88:89], v[132:133], v[228:229]
	v_pk_fma_f32 v[90:91], v[90:91], v[134:135], v[230:231]
	v_pk_fma_f32 v[76:77], v[76:77], v[136:137], v[232:233]
	v_pk_fma_f32 v[78:79], v[78:79], v[138:139], v[234:235]
	v_pk_fma_f32 v[72:73], v[72:73], v[140:141], v[152:153]
	v_pk_fma_f32 v[74:75], v[74:75], v[142:143], v[154:155]
	v_mul_f32_e32 v150, v93, v93
	v_mul_f32_e32 v151, v89, v89
	v_mul_f32_e32 v173, v77, v77
	v_fmac_f32_e32 v150, v92, v92
	v_fmac_f32_e32 v151, v88, v88
	v_mul_f32_e32 v236, v73, v73
	v_fmac_f32_e32 v173, v76, v76
	v_fmac_f32_e32 v150, v94, v94
	v_fmac_f32_e32 v151, v90, v90
	v_fmac_f32_e32 v236, v72, v72
	v_fmac_f32_e32 v173, v78, v78
	v_fmac_f32_e32 v150, v95, v95
	v_fmac_f32_e32 v151, v91, v91
	v_fmac_f32_e32 v236, v74, v74
	v_fmac_f32_e32 v173, v79, v79
	v_add_f32_e32 v150, v150, v151
	v_add_f32_e32 v150, v150, v173
	v_fmac_f32_e32 v236, v75, v75
	v_add_f32_e32 v150, v150, v236
	ds_bpermute_b32 v151, v148, v150
	s_waitcnt lgkmcnt(0)
;     __device__ __forceinline__ void operator()(const f32x4 (&acc)[2][2][4][2], const Unit& u, int wr, int wc, int fr, int fq) const {
;     ...
; #pragma unroll
;         for (int ai = 0; ai < 2; ++ai)
; #pragma unroll
;             for (int m = 0; m < 4; ++m) { const int ro = roff + (ai * HALF + m * 16) * D; float ps = 0.f;
; #pragma unroll
;                 for (int bj = 0; bj < 2; ++bj)
; #pragma unroll
;                     for (int n = 0; n < 2; ++n) { const int o = bj * HALF + n * 16; const f32x4 rv = *(const f32x4*)(res0 + (ro + o)), gv = *(const f32x4*)(gp + (col0 + o));
;                         const f32x4 v = rv + gv * acc[ai][bj][m][n]; ps += v[0] * v[0] + v[1] * v[1] + v[2] * v[2] + v[3] * v[3]; }
;                 ps += __shfl_xor(ps, 16); ps += __shfl_xor(ps, 32);
;                 if (fq == 0) red[(ai * HALF + wr * 64 + m * 16 + fr) * 4 + wc] = ps; }
	v_add_f32_e32 v150, v150, v151
	ds_bpermute_b32 v151, v149, v150
	s_waitcnt lgkmcnt(0)
	v_add_f32_e32 v150, v150, v151
	s_and_saveexec_b64 s[30:31], s[0:1]
	ds_write_b32 v189, v150 offset:512
	s_or_b64 exec, exec, s[30:31]
	v_add_co_u32_e32 v176, vcc, 0x120000, v146
	s_nop 1
	v_addc_co_u32_e32 v177, vcc, 0, v147, vcc
	global_load_dwordx4 v[224:227], v[176:177], off
	global_load_dwordx4 v[228:231], v[176:177], off offset:64
	global_load_dwordx4 v[232:235], v[176:177], off offset:512
	global_load_dwordx4 v[152:155], v[176:177], off offset:576
	s_waitcnt vmcnt(8)
	v_pk_fma_f32 v[84:85], v[84:85], v[128:129], v[192:193]
	v_pk_fma_f32 v[86:87], v[86:87], v[130:131], v[194:195]
	v_pk_fma_f32 v[80:81], v[80:81], v[132:133], v[196:197]
	v_pk_fma_f32 v[82:83], v[82:83], v[134:135], v[198:199]
	v_pk_fma_f32 v[68:69], v[68:69], v[136:137], v[200:201]
	v_pk_fma_f32 v[70:71], v[70:71], v[138:139], v[202:203]
	v_pk_fma_f32 v[64:65], v[64:65], v[140:141], v[204:205]
	v_pk_fma_f32 v[66:67], v[66:67], v[142:143], v[206:207]
	v_mul_f32_e32 v150, v85, v85
	v_mul_f32_e32 v151, v81, v81
	v_mul_f32_e32 v173, v69, v69
	v_fmac_f32_e32 v150, v84, v84
	v_fmac_f32_e32 v151, v80, v80
	v_mul_f32_e32 v236, v65, v65
	v_fmac_f32_e32 v173, v68, v68
	v_fmac_f32_e32 v150, v86, v86
	v_fmac_f32_e32 v151, v82, v82
	v_fmac_f32_e32 v236, v64, v64
	v_fmac_f32_e32 v173, v70, v70
	v_fmac_f32_e32 v150, v87, v87
	v_fmac_f32_e32 v151, v83, v83
	v_fmac_f32_e32 v236, v66, v66
	v_fmac_f32_e32 v173, v71, v71
	v_add_f32_e32 v150, v150, v151
	v_add_f32_e32 v150, v150, v173
	v_fmac_f32_e32 v236, v67, v67
	v_add_f32_e32 v150, v150, v236
	ds_bpermute_b32 v151, v148, v150
	s_waitcnt lgkmcnt(0)
	v_add_f32_e32 v150, v150, v151
	ds_bpermute_b32 v151, v149, v150
	s_waitcnt lgkmcnt(0)
	v_add_f32_e32 v150, v150, v151
	s_and_saveexec_b64 s[30:31], s[0:1]
	ds_write_b32 v189, v150 offset:768
	s_or_b64 exec, exec, s[30:31]
	v_add_co_u32_e32 v176, vcc, 0x140000, v146
	s_nop 1
	v_addc_co_u32_e32 v177, vcc, 0, v147, vcc
	global_load_dwordx4 v[192:195], v[176:177], off
	global_load_dwordx4 v[196:199], v[176:177], off offset:64
	global_load_dwordx4 v[200:203], v[176:177], off offset:512
	global_load_dwordx4 v[204:207], v[176:177], off offset:576
	s_waitcnt vmcnt(8)
	v_pk_fma_f32 v[60:61], v[60:61], v[128:129], v[208:209]
	v_pk_fma_f32 v[62:63], v[62:63], v[130:131], v[210:211]
	v_pk_fma_f32 v[56:57], v[56:57], v[132:133], v[212:213]
	v_pk_fma_f32 v[58:59], v[58:59], v[134:135], v[214:215]
	v_pk_fma_f32 v[44:45], v[44:45], v[136:137], v[216:217]
	v_pk_fma_f32 v[46:47], v[46:47], v[138:139], v[218:219]
	v_pk_fma_f32 v[40:41], v[40:41], v[140:141], v[220:221]
	v_pk_fma_f32 v[42:43], v[42:43], v[142:143], v[222:223]
	v_mul_f32_e32 v150, v61, v61
	v_mul_f32_e32 v151, v57, v57
	v_mul_f32_e32 v173, v45, v45
	v_fmac_f32_e32 v150, v60, v60
	v_fmac_f32_e32 v151, v56, v56
	v_mul_f32_e32 v236, v41, v41
	v_fmac_f32_e32 v173, v44, v44
	v_fmac_f32_e32 v150, v62, v62
	v_fmac_f32_e32 v151, v58, v58
	v_fmac_f32_e32 v236, v40, v40
	v_fmac_f32_e32 v173, v46, v46
	v_fmac_f32_e32 v150, v63, v63
	v_fmac_f32_e32 v151, v59, v59
	v_fmac_f32_e32 v236, v42, v42
	v_fmac_f32_e32 v173, v47, v47
	v_add_f32_e32 v150, v150, v151
	v_add_f32_e32 v150, v150, v173
	v_fmac_f32_e32 v236, v43, v43
	v_add_f32_e32 v150, v150, v236
	ds_bpermute_b32 v151, v148, v150
	s_waitcnt lgkmcnt(0)
	v_add_f32_e32 v150, v150, v151
	ds_bpermute_b32 v151, v149, v150
	s_waitcnt lgkmcnt(0)
	v_add_f32_e32 v150, v150, v151
	s_and_saveexec_b64 s[30:31], s[0:1]
	ds_write_b32 v189, v150 offset:2048
	s_or_b64 exec, exec, s[30:31]
	v_add_co_u32_e32 v176, vcc, 0x160000, v146
	s_nop 1
	v_addc_co_u32_e32 v177, vcc, 0, v147, vcc
	global_load_dwordx4 v[208:211], v[176:177], off
	global_load_dwordx4 v[212:215], v[176:177], off offset:64
	global_load_dwordx4 v[216:219], v[176:177], off offset:512
	global_load_dwordx4 v[220:223], v[176:177], off offset:576
	s_waitcnt vmcnt(8)
;     __device__ __forceinline__ void operator()(const f32x4 (&acc)[2][2][4][2], const Unit& u, int wr, int wc, int fr, int fq) const {
;     ...
; #pragma unroll
;         for (int ai = 0; ai < 2; ++ai)
; #pragma unroll
;             for (int m = 0; m < 4; ++m) { const int ro = roff + (ai * HALF + m * 16) * D; float ps = 0.f;
; #pragma unroll
;                 for (int bj = 0; bj < 2; ++bj)
; #pragma unroll
;                     for (int n = 0; n < 2; ++n) { const int o = bj * HALF + n * 16; const f32x4 rv = *(const f32x4*)(res0 + (ro + o)), gv = *(const f32x4*)(gp + (col0 + o));
;                         const f32x4 v = rv + gv * acc[ai][bj][m][n]; ps += v[0] * v[0] + v[1] * v[1] + v[2] * v[2] + v[3] * v[3]; }
;                 ps += __shfl_xor(ps, 16); ps += __shfl_xor(ps, 32);
;                 if (fq == 0) red[(ai * HALF + wr * 64 + m * 16 + fr) * 4 + wc] = ps; }
	v_pk_fma_f32 v[52:53], v[52:53], v[128:129], v[224:225]
	v_pk_fma_f32 v[54:55], v[54:55], v[130:131], v[226:227]
	v_pk_fma_f32 v[48:49], v[48:49], v[132:133], v[228:229]
	v_pk_fma_f32 v[50:51], v[50:51], v[134:135], v[230:231]
	v_pk_fma_f32 v[36:37], v[36:37], v[136:137], v[232:233]
	v_pk_fma_f32 v[38:39], v[38:39], v[138:139], v[234:235]
	v_pk_fma_f32 v[32:33], v[32:33], v[140:141], v[152:153]
	v_pk_fma_f32 v[34:35], v[34:35], v[142:143], v[154:155]
	v_mul_f32_e32 v150, v53, v53
	v_mul_f32_e32 v151, v49, v49
	v_mul_f32_e32 v173, v37, v37
	v_fmac_f32_e32 v150, v52, v52
	v_fmac_f32_e32 v151, v48, v48
	v_mul_f32_e32 v236, v33, v33
	v_fmac_f32_e32 v173, v36, v36
	v_fmac_f32_e32 v150, v54, v54
	v_fmac_f32_e32 v151, v50, v50
	v_fmac_f32_e32 v236, v32, v32
	v_fmac_f32_e32 v173, v38, v38
	v_fmac_f32_e32 v150, v55, v55
	v_fmac_f32_e32 v151, v51, v51
	v_fmac_f32_e32 v236, v34, v34
	v_fmac_f32_e32 v173, v39, v39
	v_add_f32_e32 v150, v150, v151
	v_add_f32_e32 v150, v150, v173
	v_fmac_f32_e32 v236, v35, v35
	v_add_f32_e32 v150, v150, v236
	ds_bpermute_b32 v151, v148, v150
	s_waitcnt lgkmcnt(0)
	v_add_f32_e32 v150, v150, v151
	ds_bpermute_b32 v151, v149, v150
	s_waitcnt lgkmcnt(0)
	v_add_f32_e32 v150, v150, v151
	s_and_saveexec_b64 s[30:31], s[0:1]
	ds_write_b32 v189, v150 offset:2304
	s_or_b64 exec, exec, s[30:31]
	s_waitcnt vmcnt(4)
	v_pk_fma_f32 v[28:29], v[28:29], v[128:129], v[192:193]
	v_pk_fma_f32 v[30:31], v[30:31], v[130:131], v[194:195]
	v_pk_fma_f32 v[24:25], v[24:25], v[132:133], v[196:197]
	v_pk_fma_f32 v[26:27], v[26:27], v[134:135], v[198:199]
	v_pk_fma_f32 v[12:13], v[12:13], v[136:137], v[200:201]
	v_pk_fma_f32 v[14:15], v[14:15], v[138:139], v[202:203]
	v_pk_fma_f32 v[8:9], v[8:9], v[140:141], v[204:205]
	v_pk_fma_f32 v[10:11], v[10:11], v[142:143], v[206:207]
	v_mul_f32_e32 v150, v29, v29
	v_mul_f32_e32 v151, v25, v25
	v_mul_f32_e32 v173, v13, v13
	v_fmac_f32_e32 v150, v28, v28
	v_fmac_f32_e32 v151, v24, v24
	v_mul_f32_e32 v236, v9, v9
	v_fmac_f32_e32 v173, v12, v12
	v_fmac_f32_e32 v150, v30, v30
	v_fmac_f32_e32 v151, v26, v26
	v_fmac_f32_e32 v236, v8, v8
	v_fmac_f32_e32 v173, v14, v14
	v_fmac_f32_e32 v150, v31, v31
	v_fmac_f32_e32 v151, v27, v27
	v_fmac_f32_e32 v236, v10, v10
	v_fmac_f32_e32 v173, v15, v15
	v_add_f32_e32 v150, v150, v151
	v_add_f32_e32 v150, v150, v173
	v_fmac_f32_e32 v236, v11, v11
	v_add_f32_e32 v150, v150, v236
	ds_bpermute_b32 v151, v148, v150
	s_waitcnt lgkmcnt(0)
	v_add_f32_e32 v150, v150, v151
	ds_bpermute_b32 v151, v149, v150
	s_waitcnt lgkmcnt(0)
	v_add_f32_e32 v150, v150, v151
	s_and_saveexec_b64 s[30:31], s[0:1]
	ds_write_b32 v189, v150 offset:2560
	s_or_b64 exec, exec, s[30:31]
	s_waitcnt vmcnt(0)
	v_pk_fma_f32 v[20:21], v[20:21], v[128:129], v[208:209]
	v_pk_fma_f32 v[22:23], v[22:23], v[130:131], v[210:211]
	v_pk_fma_f32 v[16:17], v[16:17], v[132:133], v[212:213]
	v_pk_fma_f32 v[18:19], v[18:19], v[134:135], v[214:215]
	v_pk_fma_f32 v[4:5], v[4:5], v[136:137], v[216:217]
	v_pk_fma_f32 v[6:7], v[6:7], v[138:139], v[218:219]
	v_pk_fma_f32 v[0:1], v[0:1], v[140:141], v[220:221]
	v_pk_fma_f32 v[2:3], v[2:3], v[142:143], v[222:223]
	v_mul_f32_e32 v150, v21, v21
	v_mul_f32_e32 v151, v17, v17
	v_mul_f32_e32 v173, v5, v5
	v_fmac_f32_e32 v150, v20, v20
	v_fmac_f32_e32 v151, v16, v16
	v_mul_f32_e32 v236, v1, v1
	v_fmac_f32_e32 v173, v4, v4
	v_fmac_f32_e32 v150, v22, v22
	v_fmac_f32_e32 v151, v18, v18
	v_fmac_f32_e32 v236, v0, v0
	v_fmac_f32_e32 v173, v6, v6
	v_fmac_f32_e32 v150, v23, v23
	v_fmac_f32_e32 v151, v19, v19
	v_fmac_f32_e32 v236, v2, v2
	v_fmac_f32_e32 v173, v7, v7
	v_add_f32_e32 v150, v150, v151
	v_add_f32_e32 v150, v150, v173
	v_fmac_f32_e32 v236, v3, v3
	v_add_f32_e32 v150, v150, v236
	ds_bpermute_b32 v151, v148, v150
	s_waitcnt lgkmcnt(0)
	v_add_f32_e32 v150, v150, v151
	ds_bpermute_b32 v151, v149, v150
	s_waitcnt lgkmcnt(0)
	v_add_f32_e32 v150, v150, v151
	s_and_saveexec_b64 s[30:31], s[0:1]
	ds_write_b32 v189, v150 offset:2816
	s_or_b64 exec, exec, s[30:31]

;     __device__ __forceinline__ void operator()(const f32x4 (&acc)[2][2][4][2], const Unit& u, int wr, int wc, int fr, int fq) const {
;     ...
;         if (tid < 256) { float tot = 0.f; const float* sp = ssq + (size_t)(u.pm * 8) * 256 + tid;
; #pragma unroll 1
;             for (int j = 0; j < 8; ++j) { tot += __hip_atomic_load(sp, __ATOMIC_RELAXED, __HIP_MEMORY_SCOPE_AGENT); sp += 256; }
;             red[1024 + tid] = rsqrtf(tot * (1.f / D) + EPS); }
;         __syncthreads();
;         int woff = row0 * D + col0; asm volatile("" : "+v"(woff));
;         f32x4 gw[2][2], ww[2][2];
; #pragma unroll
;         for (int bj = 0; bj < 2; ++bj)
; #pragma unroll
;             for (int n = 0; n < 2; ++n) { gw[bj][n] = *(const f32x4*)(gp + (col0 + bj * HALF + n * 16)); ww[bj][n] = *(const f32x4*)(nw + (col0 + bj * HALF + n * 16)); }
; #pragma unroll
;         for (int am = 0; am < 4; ++am) { f32x4 rv[2][2][2]; float rr[2];
; #pragma unroll
;             for (int m2 = 0; m2 < 2; ++m2) { rr[m2] = red[1024 + (am >> 1) * HALF + wr * 64 + ((am & 1) * 2 + m2) * 16 + fr];
; #pragma unroll
;                 for (int bj = 0; bj < 2; ++bj)
; #pragma unroll
;                     for (int n = 0; n < 2; ++n) rv[m2][bj][n] = *(const f32x4*)(res0 + (woff + ((am >> 1) * HALF + ((am & 1) * 2 + m2) * 16) * D + bj * HALF + n * 16)); }
; #pragma unroll
;             for (int m2 = 0; m2 < 2; ++m2)
; #pragma unroll
;                 for (int bj = 0; bj < 2; ++bj)
; #pragma unroll
;                     for (int n = 0; n < 2; ++n) *(f32x4*)(out + (woff + ((am >> 1) * HALF + ((am & 1) * 2 + m2) * 16) * D + bj * HALF + n * 16)) = (rv[m2][bj][n] + gw[bj][n] * acc[am >> 1][bj][(am & 1) * 2 + m2][n]) * rr[m2] * ww[bj][n]; }
.LBB0_1181:
	s_or_b64 exec, exec, s[30:31]
	s_waitcnt lgkmcnt(0)
	s_barrier
	v_readlane_b32 s70, v245, 9
	v_readlane_b32 s71, v245, 10
	s_nop 3
	v_lshl_add_u64 v[144:145], v[174:175], 2, s[70:71]
	global_load_dwordx4 v[208:211], v[144:145], off
	global_load_dwordx4 v[212:215], v[144:145], off offset:64
	global_load_dwordx4 v[216:219], v[144:145], off offset:512
	global_load_dwordx4 v[220:223], v[144:145], off offset:576
	ds_read2_b32 v[192:193], v180 offset1:16
	ds_read2_b32 v[194:195], v180 offset0:32 offset1:48
	ds_read2_b32 v[196:197], v181 offset1:16
	ds_read2_b32 v[198:199], v181 offset0:32 offset1:48
	v_readlane_b32 s64, v245, 21
	v_readlane_b32 s65, v245, 22
	v_readlane_b32 s66, v245, 23
	v_readlane_b32 s67, v245, 24
	v_readlane_b32 s68, v245, 25
	v_readlane_b32 s69, v245, 26
	v_readlane_b32 s70, v245, 27
	v_readlane_b32 s71, v245, 28
	v_readlane_b32 s72, v245, 29
	v_readlane_b32 s73, v245, 30
	v_readlane_b32 s74, v245, 31
	v_readlane_b32 s75, v245, 32
	v_readlane_b32 s76, v245, 33
	v_readlane_b32 s77, v245, 34
	v_readlane_b32 s78, v245, 35
	v_readlane_b32 s79, v245, 36
	s_nop 3
	s_mov_b64 s[26:27], s[78:79]
	s_mov_b64 s[34:35], 0
	s_mov_b64 s[30:31], s[78:79]
	v_ashrrev_i32_e32 v173, 31, v172
	v_lshlrev_b64 v[224:225], 2, v[172:173]
	v_lshl_add_u64 v[224:225], s[26:27], 0, v[224:225]
	s_waitcnt vmcnt(0) lgkmcnt(0)
	v_pk_mul_f32 v[124:125], v[192:193], v[124:125] op_sel_hi:[0,1]
	v_pk_mul_f32 v[126:127], v[192:193], v[126:127] op_sel_hi:[0,1]
	v_pk_mul_f32 v[124:125], v[208:209], v[124:125]
	v_pk_mul_f32 v[126:127], v[210:211], v[126:127]
	global_store_dwordx4 v[224:225], v[124:127], off
	v_pk_mul_f32 v[120:121], v[192:193], v[120:121] op_sel_hi:[0,1]
	v_pk_mul_f32 v[122:123], v[192:193], v[122:123] op_sel_hi:[0,1]
	v_pk_mul_f32 v[120:121], v[212:213], v[120:121]
	v_pk_mul_f32 v[122:123], v[214:215], v[122:123]
	global_store_dwordx4 v[224:225], v[120:123], off offset:64
	v_pk_mul_f32 v[108:109], v[192:193], v[108:109] op_sel_hi:[0,1]
	v_pk_mul_f32 v[110:111], v[192:193], v[110:111] op_sel_hi:[0,1]
	v_pk_mul_f32 v[108:109], v[216:217], v[108:109]
	v_pk_mul_f32 v[110:111], v[218:219], v[110:111]
	global_store_dwordx4 v[224:225], v[108:111], off offset:512
	v_pk_mul_f32 v[104:105], v[192:193], v[104:105] op_sel_hi:[0,1]
	v_pk_mul_f32 v[106:107], v[192:193], v[106:107] op_sel_hi:[0,1]
	v_pk_mul_f32 v[104:105], v[220:221], v[104:105]
	v_pk_mul_f32 v[106:107], v[222:223], v[106:107]
	global_store_dwordx4 v[224:225], v[104:107], off offset:576
	v_add_co_u32_e32 v226, vcc, 0x20000, v224
	s_nop 1
	v_addc_co_u32_e32 v227, vcc, 0, v225, vcc
	v_pk_mul_f32 v[116:117], v[192:193], v[116:117] op_sel:[1,0]
	v_pk_mul_f32 v[118:119], v[192:193], v[118:119] op_sel:[1,0]
	v_pk_mul_f32 v[116:117], v[208:209], v[116:117]
	v_pk_mul_f32 v[118:119], v[210:211], v[118:119]
	global_store_dwordx4 v[226:227], v[116:119], off
	v_pk_mul_f32 v[112:113], v[192:193], v[112:113] op_sel:[1,0]
	v_pk_mul_f32 v[114:115], v[192:193], v[114:115] op_sel:[1,0]
	v_pk_mul_f32 v[112:113], v[212:213], v[112:113]
	v_pk_mul_f32 v[114:115], v[214:215], v[114:115]
	global_store_dwordx4 v[226:227], v[112:115], off offset:64
	v_pk_mul_f32 v[100:101], v[192:193], v[100:101] op_sel:[1,0]
	v_pk_mul_f32 v[102:103], v[192:193], v[102:103] op_sel:[1,0]
	v_pk_mul_f32 v[100:101], v[216:217], v[100:101]
	v_pk_mul_f32 v[102:103], v[218:219], v[102:103]
	global_store_dwordx4 v[226:227], v[100:103], off offset:512
	v_pk_mul_f32 v[96:97], v[192:193], v[96:97] op_sel:[1,0]
	v_pk_mul_f32 v[98:99], v[192:193], v[98:99] op_sel:[1,0]
	v_pk_mul_f32 v[96:97], v[220:221], v[96:97]
	v_pk_mul_f32 v[98:99], v[222:223], v[98:99]
	global_store_dwordx4 v[226:227], v[96:99], off offset:576
	v_add_co_u32_e32 v226, vcc, 0x40000, v224
	s_nop 1
	v_addc_co_u32_e32 v227, vcc, 0, v225, vcc
	v_pk_mul_f32 v[92:93], v[194:195], v[92:93] op_sel_hi:[0,1]
	v_pk_mul_f32 v[94:95], v[194:195], v[94:95] op_sel_hi:[0,1]
	v_pk_mul_f32 v[92:93], v[208:209], v[92:93]
	v_pk_mul_f32 v[94:95], v[210:211], v[94:95]
	global_store_dwordx4 v[226:227], v[92:95], off
	v_pk_mul_f32 v[88:89], v[194:195], v[88:89] op_sel_hi:[0,1]
	v_pk_mul_f32 v[90:91], v[194:195], v[90:91] op_sel_hi:[0,1]
	v_pk_mul_f32 v[88:89], v[212:213], v[88:89]
	v_pk_mul_f32 v[90:91], v[214:215], v[90:91]
	global_store_dwordx4 v[226:227], v[88:91], off offset:64
	v_pk_mul_f32 v[76:77], v[194:195], v[76:77] op_sel_hi:[0,1]
	v_pk_mul_f32 v[78:79], v[194:195], v[78:79] op_sel_hi:[0,1]
	v_pk_mul_f32 v[76:77], v[216:217], v[76:77]
	v_pk_mul_f32 v[78:79], v[218:219], v[78:79]
	global_store_dwordx4 v[226:227], v[76:79], off offset:512
	v_pk_mul_f32 v[72:73], v[194:195], v[72:73] op_sel_hi:[0,1]
	v_pk_mul_f32 v[74:75], v[194:195], v[74:75] op_sel_hi:[0,1]
	v_pk_mul_f32 v[72:73], v[220:221], v[72:73]
	v_pk_mul_f32 v[74:75], v[222:223], v[74:75]
	global_store_dwordx4 v[226:227], v[72:75], off offset:576
	v_add_co_u32_e32 v226, vcc, 0x60000, v224
	s_nop 1
	v_addc_co_u32_e32 v227, vcc, 0, v225, vcc
	v_pk_mul_f32 v[84:85], v[194:195], v[84:85] op_sel:[1,0]
	v_pk_mul_f32 v[86:87], v[194:195], v[86:87] op_sel:[1,0]
	v_pk_mul_f32 v[84:85], v[208:209], v[84:85]
	v_pk_mul_f32 v[86:87], v[210:211], v[86:87]
	global_store_dwordx4 v[226:227], v[84:87], off
	v_pk_mul_f32 v[80:81], v[194:195], v[80:81] op_sel:[1,0]
;     __device__ __forceinline__ void operator()(const f32x4 (&acc)[2][2][4][2], const Unit& u, int wr, int wc, int fr, int fq) const {
;     ...
; #pragma unroll
;             for (int m2 = 0; m2 < 2; ++m2)
; #pragma unroll
;                 for (int bj = 0; bj < 2; ++bj)
; #pragma unroll
;                     for (int n = 0; n < 2; ++n) *(f32x4*)(out + (woff + ((am >> 1) * HALF + ((am & 1) * 2 + m2) * 16) * D + bj * HALF + n * 16)) = (rv[m2][bj][n] + gw[bj][n] * acc[am >> 1][bj][(am & 1) * 2 + m2][n]) * rr[m2] * ww[bj][n]; }
	v_pk_mul_f32 v[82:83], v[194:195], v[82:83] op_sel:[1,0]
	v_pk_mul_f32 v[80:81], v[212:213], v[80:81]
	v_pk_mul_f32 v[82:83], v[214:215], v[82:83]
	global_store_dwordx4 v[226:227], v[80:83], off offset:64
	v_pk_mul_f32 v[68:69], v[194:195], v[68:69] op_sel:[1,0]
	v_pk_mul_f32 v[70:71], v[194:195], v[70:71] op_sel:[1,0]
	v_pk_mul_f32 v[68:69], v[216:217], v[68:69]
	v_pk_mul_f32 v[70:71], v[218:219], v[70:71]
	global_store_dwordx4 v[226:227], v[68:71], off offset:512
	v_pk_mul_f32 v[64:65], v[194:195], v[64:65] op_sel:[1,0]
	v_pk_mul_f32 v[66:67], v[194:195], v[66:67] op_sel:[1,0]
	v_pk_mul_f32 v[64:65], v[220:221], v[64:65]
	v_pk_mul_f32 v[66:67], v[222:223], v[66:67]
	global_store_dwordx4 v[226:227], v[64:67], off offset:576
	v_add_co_u32_e32 v226, vcc, 0x100000, v224
	s_nop 1
	v_addc_co_u32_e32 v227, vcc, 0, v225, vcc
	v_pk_mul_f32 v[60:61], v[196:197], v[60:61] op_sel_hi:[0,1]
	v_pk_mul_f32 v[62:63], v[196:197], v[62:63] op_sel_hi:[0,1]
	v_pk_mul_f32 v[60:61], v[208:209], v[60:61]
	v_pk_mul_f32 v[62:63], v[210:211], v[62:63]
	global_store_dwordx4 v[226:227], v[60:63], off
	v_pk_mul_f32 v[56:57], v[196:197], v[56:57] op_sel_hi:[0,1]
	v_pk_mul_f32 v[58:59], v[196:197], v[58:59] op_sel_hi:[0,1]
	v_pk_mul_f32 v[56:57], v[212:213], v[56:57]
	v_pk_mul_f32 v[58:59], v[214:215], v[58:59]
	global_store_dwordx4 v[226:227], v[56:59], off offset:64
	v_pk_mul_f32 v[44:45], v[196:197], v[44:45] op_sel_hi:[0,1]
	v_pk_mul_f32 v[46:47], v[196:197], v[46:47] op_sel_hi:[0,1]
	v_pk_mul_f32 v[44:45], v[216:217], v[44:45]
	v_pk_mul_f32 v[46:47], v[218:219], v[46:47]
	global_store_dwordx4 v[226:227], v[44:47], off offset:512
	v_pk_mul_f32 v[40:41], v[196:197], v[40:41] op_sel_hi:[0,1]
	v_pk_mul_f32 v[42:43], v[196:197], v[42:43] op_sel_hi:[0,1]
	v_pk_mul_f32 v[40:41], v[220:221], v[40:41]
	v_pk_mul_f32 v[42:43], v[222:223], v[42:43]
	global_store_dwordx4 v[226:227], v[40:43], off offset:576
	v_add_co_u32_e32 v226, vcc, 0x120000, v224
	s_nop 1
	v_addc_co_u32_e32 v227, vcc, 0, v225, vcc
	v_pk_mul_f32 v[52:53], v[196:197], v[52:53] op_sel:[1,0]
	v_pk_mul_f32 v[54:55], v[196:197], v[54:55] op_sel:[1,0]
	v_pk_mul_f32 v[52:53], v[208:209], v[52:53]
	v_pk_mul_f32 v[54:55], v[210:211], v[54:55]
	global_store_dwordx4 v[226:227], v[52:55], off
	v_pk_mul_f32 v[48:49], v[196:197], v[48:49] op_sel:[1,0]
	v_pk_mul_f32 v[50:51], v[196:197], v[50:51] op_sel:[1,0]
	v_pk_mul_f32 v[48:49], v[212:213], v[48:49]
	v_pk_mul_f32 v[50:51], v[214:215], v[50:51]
	global_store_dwordx4 v[226:227], v[48:51], off offset:64
	v_pk_mul_f32 v[36:37], v[196:197], v[36:37] op_sel:[1,0]
	v_pk_mul_f32 v[38:39], v[196:197], v[38:39] op_sel:[1,0]
	v_pk_mul_f32 v[36:37], v[216:217], v[36:37]
	v_pk_mul_f32 v[38:39], v[218:219], v[38:39]
	global_store_dwordx4 v[226:227], v[36:39], off offset:512
	v_pk_mul_f32 v[32:33], v[196:197], v[32:33] op_sel:[1,0]
	v_pk_mul_f32 v[34:35], v[196:197], v[34:35] op_sel:[1,0]
	v_pk_mul_f32 v[32:33], v[220:221], v[32:33]
	v_pk_mul_f32 v[34:35], v[222:223], v[34:35]
	global_store_dwordx4 v[226:227], v[32:35], off offset:576
	v_add_co_u32_e32 v226, vcc, 0x140000, v224
	s_nop 1
	v_addc_co_u32_e32 v227, vcc, 0, v225, vcc
	v_pk_mul_f32 v[28:29], v[198:199], v[28:29] op_sel_hi:[0,1]
	v_pk_mul_f32 v[30:31], v[198:199], v[30:31] op_sel_hi:[0,1]
	v_pk_mul_f32 v[28:29], v[208:209], v[28:29]
	v_pk_mul_f32 v[30:31], v[210:211], v[30:31]
	global_store_dwordx4 v[226:227], v[28:31], off
	v_pk_mul_f32 v[24:25], v[198:199], v[24:25] op_sel_hi:[0,1]
	v_pk_mul_f32 v[26:27], v[198:199], v[26:27] op_sel_hi:[0,1]
	v_pk_mul_f32 v[24:25], v[212:213], v[24:25]
	v_pk_mul_f32 v[26:27], v[214:215], v[26:27]
	global_store_dwordx4 v[226:227], v[24:27], off offset:64
	v_pk_mul_f32 v[12:13], v[198:199], v[12:13] op_sel_hi:[0,1]
	v_pk_mul_f32 v[14:15], v[198:199], v[14:15] op_sel_hi:[0,1]
	v_pk_mul_f32 v[12:13], v[216:217], v[12:13]
	v_pk_mul_f32 v[14:15], v[218:219], v[14:15]
	global_store_dwordx4 v[226:227], v[12:15], off offset:512
	v_pk_mul_f32 v[8:9], v[198:199], v[8:9] op_sel_hi:[0,1]
	v_pk_mul_f32 v[10:11], v[198:199], v[10:11] op_sel_hi:[0,1]
	v_pk_mul_f32 v[8:9], v[220:221], v[8:9]
	v_pk_mul_f32 v[10:11], v[222:223], v[10:11]
	global_store_dwordx4 v[226:227], v[8:11], off offset:576
	v_add_co_u32_e32 v226, vcc, 0x160000, v224
	s_nop 1
	v_addc_co_u32_e32 v227, vcc, 0, v225, vcc
	v_pk_mul_f32 v[20:21], v[198:199], v[20:21] op_sel:[1,0]
	v_pk_mul_f32 v[22:23], v[198:199], v[22:23] op_sel:[1,0]
	v_pk_mul_f32 v[20:21], v[208:209], v[20:21]
	v_pk_mul_f32 v[22:23], v[210:211], v[22:23]
	global_store_dwordx4 v[226:227], v[20:23], off
	v_pk_mul_f32 v[16:17], v[198:199], v[16:17] op_sel:[1,0]
	v_pk_mul_f32 v[18:19], v[198:199], v[18:19] op_sel:[1,0]
	v_pk_mul_f32 v[16:17], v[212:213], v[16:17]
	v_pk_mul_f32 v[18:19], v[214:215], v[18:19]
	global_store_dwordx4 v[226:227], v[16:19], off offset:64
	v_pk_mul_f32 v[4:5], v[198:199], v[4:5] op_sel:[1,0]
	v_pk_mul_f32 v[6:7], v[198:199], v[6:7] op_sel:[1,0]
	v_pk_mul_f32 v[4:5], v[216:217], v[4:5]
	v_pk_mul_f32 v[6:7], v[218:219], v[6:7]
	global_store_dwordx4 v[226:227], v[4:7], off offset:512
	v_pk_mul_f32 v[128:129], v[198:199], v[0:1] op_sel:[1,0]
	v_pk_mul_f32 v[130:131], v[198:199], v[2:3] op_sel:[1,0]
	v_pk_mul_f32 v[128:129], v[220:221], v[128:129]
	v_pk_mul_f32 v[130:131], v[222:223], v[130:131]
